# fixup2_both_rows_per_thread
# baseline (speedup 1.0000x reference)
.LBB0_880:
	s_or_b64 exec, exec, s[2:3]
	s_mov_b64 s[8:9], s[84:85]
	v_mov_b32_e32 v0, v165
	v_readlane_b32 s2, v253, 3
	s_waitcnt lgkmcnt(0)
	s_barrier
	s_nop 0
	v_add_u32_e32 v64, s2, v0
	s_mov_b32 s2, 0x58000
	v_cmp_gt_i32_e32 vcc, s2, v64
	s_and_saveexec_b64 s[2:3], vcc
	s_cbranch_execz .LBB0_897
	s_load_dwordx2 s[10:11], s[8:9], 0x90
	s_load_dwordx4 s[4:7], s[8:9], 0x68
	v_lshlrev_b32_e32 v65, 2, v64
	s_mov_b64 s[26:27], 0
	s_waitcnt lgkmcnt(0)
	s_add_u32 s8, s10, 0x8500000
	s_addc_u32 s9, s11, 0
	s_add_u32 s10, s10, 0xb100000
	s_addc_u32 s11, s11, 0
	s_add_u32 s12, s4, s48
	s_addc_u32 s13, s5, 0
	s_add_u32 s6, s6, s33
	s_addc_u32 s7, s7, 0
	s_add_u32 s14, s12, 0x5800
	s_addc_u32 s15, s13, 0
	s_add_u32 s16, s12, 0xb000
	s_addc_u32 s17, s13, 0
	s_add_u32 s18, s6, 0x2c00
	s_addc_u32 s19, s7, 0
	s_add_u32 s20, s12, 0x2c00
	s_addc_u32 s21, s13, 0
	s_add_u32 s22, s12, 0x8400
	s_addc_u32 s23, s13, 0
	s_add_u32 s24, s12, 0xdc00
	s_addc_u32 s25, s13, 0
	s_lshl_b32 s33, s94, 2
	s_branch .LBB0_883
.LBB0_883:
	s_mov_b32 s4, 0x2e8ba2e9
	v_mul_hi_i32 v0, v64, s4
	v_ashrrev_i32_e32 v2, 7, v0
	v_lshrrev_b32_e32 v3, 31, v0
	v_add_u32_e32 v66, v2, v3
	v_mul_i32_i24_e32 v2, 0x2c0, v66
	v_and_b32_e32 v0, 31, v66
	v_lshlrev_b32_e32 v2, 2, v2
	v_cmp_ne_u32_e64 s[4:5], 0, v0
	v_add_u32_e32 v0, -1, v66
	v_sub_u32_e32 v60, v65, v2
	v_mul_hi_i32_i24_e32 v3, 0x16000, v66
	v_mul_i32_i24_e32 v2, 0x16000, v66
	v_mul_hi_i32_i24_e32 v5, 0x16000, v0
	v_mul_i32_i24_e32 v4, 0x16000, v0
	v_lshl_add_u64 v[2:3], s[8:9], 0, v[2:3]
	v_lshl_add_u64 v[24:25], s[8:9], 0, v[4:5]
	v_ashrrev_i32_e32 v61, 31, v60
	v_lshl_add_u64 v[2:3], v[60:61], 2, v[2:3]
	v_lshl_add_u64 v[24:25], v[60:61], 2, v[24:25]
	s_mov_b64 s[28:29], 0x2c00
	s_mov_b64 s[30:31], 0xb000
	v_lshl_add_u64 v[80:81], s[28:29], 0, v[2:3]
	v_lshl_add_u64 v[86:87], s[30:31], 0, v[24:25]
	global_load_dwordx4 v[4:7], v[2:3], off
	v_lshl_add_u64 v[82:83], s[28:29], 0, v[80:81]
	global_load_dwordx4 v[8:11], v[80:81], off
	v_lshl_add_u64 v[88:89], s[28:29], 0, v[86:87]
	global_load_dwordx4 v[20:23], v[86:87], off
	v_lshl_add_u64 v[84:85], s[28:29], 0, v[82:83]
	global_load_dwordx4 v[12:15], v[82:83], off
	v_lshl_add_u64 v[90:91], s[28:29], 0, v[88:89]
	global_load_dwordx4 v[28:31], v[88:89], off
	global_load_dwordx4 v[16:19], v[84:85], off
	v_lshl_add_u64 v[92:93], s[28:29], 0, v[90:91]
	global_load_dwordx4 v[32:35], v[90:91], off
	global_load_dwordx4 v[36:39], v[92:93], off
	v_lshlrev_b64 v[94:95], 2, v[60:61]
	v_lshl_add_u64 v[96:97], s[6:7], 0, v[94:95]
	v_lshl_add_u64 v[98:99], s[18:19], 0, v[94:95]
	global_load_dwordx4 v[40:43], v[96:97], off
	global_load_dwordx4 v[44:47], v[98:99], off
	v_lshl_add_u64 v[96:97], s[12:13], 0, v[94:95]
	v_lshl_add_u64 v[98:99], s[20:21], 0, v[94:95]
	global_load_dwordx4 v[48:51], v[96:97], off
	global_load_dwordx4 v[52:55], v[98:99], off
	v_lshl_add_u64 v[96:97], s[14:15], 0, v[94:95]
	v_lshl_add_u64 v[98:99], s[22:23], 0, v[94:95]
	global_load_dwordx4 v[56:59], v[96:97], off
	global_load_dwordx4 v[68:71], v[98:99], off
	v_lshl_add_u64 v[96:97], s[16:17], 0, v[94:95]
	v_lshl_add_u64 v[98:99], s[24:25], 0, v[94:95]
	global_load_dwordx4 v[72:75], v[96:97], off
	global_load_dwordx4 v[76:79], v[98:99], off
	v_add_u32_e32 v64, s94, v64
	v_add_u32_e32 v65, s33, v65
	s_waitcnt vmcnt(0)
	v_cndmask_b32_e64 v20, 0, v20, s[4:5]
	v_cndmask_b32_e64 v21, 0, v21, s[4:5]
	v_cndmask_b32_e64 v22, 0, v22, s[4:5]
	v_cndmask_b32_e64 v23, 0, v23, s[4:5]
	v_cndmask_b32_e64 v28, 0, v28, s[4:5]
	v_cndmask_b32_e64 v29, 0, v29, s[4:5]
	v_cndmask_b32_e64 v30, 0, v30, s[4:5]
	v_cndmask_b32_e64 v31, 0, v31, s[4:5]
	v_cndmask_b32_e64 v32, 0, v32, s[4:5]
	v_cndmask_b32_e64 v33, 0, v33, s[4:5]
	v_cndmask_b32_e64 v34, 0, v34, s[4:5]
	v_cndmask_b32_e64 v35, 0, v35, s[4:5]
	v_cndmask_b32_e64 v36, 0, v36, s[4:5]
	v_cndmask_b32_e64 v37, 0, v37, s[4:5]
	v_cndmask_b32_e64 v38, 0, v38, s[4:5]
	v_cndmask_b32_e64 v39, 0, v39, s[4:5]
	v_fma_f32 v80, v48, v20, v40
	v_fma_f32 v84, v52, v28, v44
	v_fma_f32 v88, v48, v32, v40
	v_fma_f32 v92, v52, v36, v44
	v_fma_f32 v81, v49, v21, v41
	v_fma_f32 v85, v53, v29, v45
	v_fma_f32 v89, v49, v33, v41
	v_fma_f32 v93, v53, v37, v45
	v_fma_f32 v82, v50, v22, v42
	v_fma_f32 v86, v54, v30, v46
	v_fma_f32 v90, v50, v34, v42
	v_fma_f32 v94, v54, v38, v46
	v_fma_f32 v83, v51, v23, v43
	v_fma_f32 v87, v55, v31, v47
	v_fma_f32 v91, v51, v35, v43
	v_fma_f32 v95, v55, v39, v47
	v_fma_f32 v80, v56, v32, v80
	v_fma_f32 v84, v68, v36, v84
	v_fma_f32 v88, v56, v4, v88
	v_fma_f32 v92, v68, v8, v92
	v_fma_f32 v81, v57, v33, v81
	v_fma_f32 v85, v69, v37, v85
	v_fma_f32 v89, v57, v5, v89
	v_fma_f32 v93, v69, v9, v93
	v_fma_f32 v82, v58, v34, v82
	v_fma_f32 v86, v70, v38, v86
	v_fma_f32 v90, v58, v6, v90
	v_fma_f32 v94, v70, v10, v94
	v_fma_f32 v83, v59, v35, v83
	v_fma_f32 v87, v71, v39, v87
	v_fma_f32 v91, v59, v7, v91
	v_fma_f32 v95, v71, v11, v95
	v_fma_f32 v80, v72, v4, v80
	v_fma_f32 v84, v76, v8, v84
	v_fma_f32 v88, v72, v12, v88
	v_fma_f32 v92, v76, v16, v92
	v_fma_f32 v81, v73, v5, v81
	v_fma_f32 v85, v77, v9, v85
	v_fma_f32 v89, v73, v13, v89
	v_fma_f32 v93, v77, v17, v93
	v_fma_f32 v82, v74, v6, v82
	v_fma_f32 v86, v78, v10, v86
	v_fma_f32 v90, v74, v14, v90
	v_fma_f32 v94, v78, v18, v94
	v_fma_f32 v83, v75, v7, v83
	v_fma_f32 v87, v79, v11, v87
	v_fma_f32 v91, v75, v15, v91
	v_fma_f32 v95, v79, v19, v95
	v_mul_f32_e32 v20, 0xbfb8aa3b, v80
	v_mul_f32_e32 v21, 0xbfb8aa3b, v81
	v_mul_f32_e32 v22, 0xbfb8aa3b, v82
	v_mul_f32_e32 v23, 0xbfb8aa3b, v83
	v_mul_f32_e32 v28, 0xbfb8aa3b, v88
	v_mul_f32_e32 v29, 0xbfb8aa3b, v89
	v_mul_f32_e32 v30, 0xbfb8aa3b, v90
	v_mul_f32_e32 v31, 0xbfb8aa3b, v91
	v_exp_f32_e32 v20, v20
	v_exp_f32_e32 v21, v21
	v_exp_f32_e32 v22, v22
	v_exp_f32_e32 v23, v23
	v_exp_f32_e32 v28, v28
	v_exp_f32_e32 v29, v29
	v_exp_f32_e32 v30, v30
	v_exp_f32_e32 v31, v31
	v_add_f32_e32 v20, 1.0, v20
	v_add_f32_e32 v21, 1.0, v21
	v_add_f32_e32 v22, 1.0, v22
	v_add_f32_e32 v23, 1.0, v23
	v_add_f32_e32 v28, 1.0, v28
	v_add_f32_e32 v29, 1.0, v29
	v_add_f32_e32 v30, 1.0, v30
	v_add_f32_e32 v31, 1.0, v31
	v_rcp_f32_e32 v20, v20
	v_rcp_f32_e32 v21, v21
	v_rcp_f32_e32 v22, v22
	v_rcp_f32_e32 v23, v23
	v_rcp_f32_e32 v28, v28
	v_rcp_f32_e32 v29, v29
	v_rcp_f32_e32 v30, v30
	v_rcp_f32_e32 v31, v31
	v_mul_f32_e32 v20, v80, v20
	v_mul_f32_e32 v21, v81, v21
	v_mul_f32_e32 v22, v82, v22
	v_mul_f32_e32 v23, v83, v23
	v_mul_f32_e32 v28, v88, v28
	v_mul_f32_e32 v29, v89, v29
	v_mul_f32_e32 v30, v90, v30
	v_mul_f32_e32 v31, v91, v31
	v_mul_f32_e32 v20, v84, v20
	v_mul_f32_e32 v21, v85, v21
	v_mul_f32_e32 v22, v86, v22
	v_mul_f32_e32 v23, v87, v23
	v_mul_f32_e32 v28, v92, v28
	v_mul_f32_e32 v29, v93, v29
	v_mul_f32_e32 v30, v94, v30
	v_mul_f32_e32 v31, v95, v31
	v_cvt_pk_bf16_f32 v2, v20, v21
	v_cvt_pk_bf16_f32 v3, v22, v23
	v_cvt_pk_bf16_f32 v6, v28, v29
	v_cvt_pk_bf16_f32 v7, v30, v31
	v_lshlrev_b32_e32 v0, 6, v66
	s_movk_i32 s4, 0x1600
	v_mov_b64_e32 v[4:5], s[10:11]
	v_mad_i64_i32 v[4:5], s[4:5], v0, s4, v[4:5]
	s_mov_b64 s[28:29], 0x1600
	s_mov_b32 s4, 0x57fff
	v_lshl_add_u64 v[4:5], v[60:61], 1, v[4:5]
	v_cmp_lt_i32_e32 vcc, s4, v64
	v_lshl_add_u64 v[8:9], s[28:29], 0, v[4:5]
	s_or_b64 s[26:27], vcc, s[26:27]
	global_store_dwordx2 v[4:5], v[2:3], off
	global_store_dwordx2 v[8:9], v[6:7], off
	s_andn2_b64 exec, exec, s[26:27]
	s_cbranch_execnz .LBB0_883
